# attention K/k_pe LDS-DMAs issued at the start of the QK^T segment (saddr form, one VGPR offset), out of the MFMA-idle stretch between QK^T and PV
# speedup vs baseline: 1.0115x; 1.0028x over previous
.LBB0_561:
	ds_read_b128 v[64:67], v189 offset:49152
	ds_read_b128 v[68:71], v189 offset:57344
	ds_read_b128 v[210:213], v190 offset:49152
	ds_read_b128 v[218:221], v190 offset:57344
	s_add_i32 s0, 0, 0x12000
	s_waitcnt lgkmcnt(3)
	v_mfma_f32_32x32x16_bf16 v[80:95], v[64:67], v[120:123], 0
	v_xor_b32_e32 v241, v243, v158
	s_add_u32 s100, s64, 0x34e80000
	s_addc_u32 s101, s65, 0
	s_lshl_b32 m0, s33, 4
	s_add_i32 m0, m0, 0x8000
	s_nop 0
	global_load_lds_dwordx4 v241, s[100:101]
	s_add_u32 s100, s64, 0x34ea0000
	s_addc_u32 s101, s65, 0
	s_add_i32 m0, m0, 0x2000
	s_nop 0
	global_load_lds_dwordx4 v241, s[100:101]
	v_xor_b32_e32 v241, v242, v170
	s_add_u32 s100, s64, 0x1ea04000
	s_addc_u32 s101, s65, 0
	s_add_i32 m0, m0, 0x6000
	s_nop 0
	global_load_lds_dwordx4 v241, s[100:101]
	v_exp_f32_e32 v175, v175
	v_exp_f32_e32 v217, v217
	v_add_f32_e32 v148, 0, v175
	s_waitcnt lgkmcnt(2)
	v_mfma_f32_32x32x16_bf16 v[64:79], v[68:71], v[120:123], 0
	v_exp_f32_e32 v149, v149
	v_add_f32_e32 v148, v217, v148
	v_exp_f32_e32 v216, v216
	s_waitcnt lgkmcnt(1)
	v_mfma_f32_32x32x16_bf16 v[80:95], v[210:213], v[124:127], v[80:95]
	v_add_f32_e32 v148, v149, v148
	v_exp_f32_e32 v150, v150
	v_add_f32_e32 v148, v216, v148
	s_waitcnt lgkmcnt(0)
	v_mfma_f32_32x32x16_bf16 v[64:79], v[218:221], v[124:127], v[64:79]
	ds_read_b128 v[210:213], v191 offset:49152
	ds_read_b128 v[218:221], v191 offset:57344
	v_exp_f32_e32 v174, v174
	v_add_f32_e32 v148, v150, v148
	v_exp_f32_e32 v151, v151
	v_add_f32_e32 v148, v174, v148
	s_waitcnt lgkmcnt(1)
	v_mfma_f32_32x32x16_bf16 v[80:95], v[210:213], v[116:119], v[80:95]
	v_exp_f32_e32 v173, v173
	v_add_f32_e32 v148, v151, v148
	v_exp_f32_e32 v154, v154
	s_waitcnt lgkmcnt(0)
	v_mfma_f32_32x32x16_bf16 v[64:79], v[218:221], v[116:119], v[64:79]
	ds_read_b128 v[210:213], v192 offset:49152
	ds_read_b128 v[218:221], v192 offset:57344
	v_add_f32_e32 v148, v173, v148
	v_exp_f32_e32 v172, v172
	v_add_f32_e32 v148, v154, v148
	s_waitcnt lgkmcnt(1)
	v_mfma_f32_32x32x16_bf16 v[80:95], v[210:213], v[112:115], v[80:95]
	v_exp_f32_e32 v153, v153
	v_add_f32_e32 v148, v172, v148
	v_exp_f32_e32 v155, v155
	v_add_f32_e32 v148, v153, v148
	s_waitcnt lgkmcnt(0)
	v_mfma_f32_32x32x16_bf16 v[64:79], v[218:221], v[112:115], v[64:79]
	ds_read_b128 v[210:213], v193 offset:49152
	ds_read_b128 v[218:221], v193 offset:57344
	ds_read_b128 v[232:235], v194 offset:49152
	ds_read_b128 v[236:239], v194 offset:57344
	v_exp_f32_e32 v145, v145
	v_add_f32_e32 v148, v155, v148
	v_exp_f32_e32 v140, v140
	s_waitcnt lgkmcnt(3)
	v_mfma_f32_32x32x16_bf16 v[80:95], v[210:213], v[108:111], v[80:95]
	v_exp_f32_e32 v147, v147
	v_add_f32_e32 v148, v145, v148
	v_exp_f32_e32 v141, v141
	s_waitcnt lgkmcnt(2)
	v_mfma_f32_32x32x16_bf16 v[64:79], v[218:221], v[108:111], v[64:79]
	ds_read_b128 v[210:213], v195 offset:49152
	ds_read_b128 v[218:221], v195 offset:57344
	v_exp_f32_e32 v144, v144
	v_add_f32_e32 v148, v147, v148
	v_exp_f32_e32 v138, v138
	v_exp_f32_e32 v146, v146
	s_waitcnt lgkmcnt(3)
	v_mfma_f32_32x32x16_bf16 v[80:95], v[232:235], v[104:107], v[80:95]
	v_add_f32_e32 v148, v144, v148
	v_exp_f32_e32 v139, v139
	v_add_f32_e32 v148, v146, v148
	s_waitcnt lgkmcnt(2)
	v_mfma_f32_32x32x16_bf16 v[64:79], v[236:239], v[104:107], v[64:79]
	ds_read_b128 v[232:235], v196 offset:49152
	ds_read_b128 v[236:239], v196 offset:57344
	v_exp_f32_e32 v132, v132
	v_add_f32_e32 v148, v140, v148
	v_exp_f32_e32 v133, v133
	s_waitcnt lgkmcnt(3)
	v_mfma_f32_32x32x16_bf16 v[80:95], v[210:213], v[100:103], v[80:95]
	v_add_u32_e32 v230, s0, v198
	v_add_u32_e32 v231, s0, v200
	v_add_f32_e32 v148, v141, v148
	v_exp_f32_e32 v130, v130
	v_add_f32_e32 v148, v138, v148
	v_exp_f32_e32 v131, v131
	s_waitcnt lgkmcnt(2)
	v_mfma_f32_32x32x16_bf16 v[64:79], v[218:221], v[100:103], v[64:79]
	ds_read_b128 v[210:213], v230
	ds_read_b128 v[218:221], v230 offset:4096
	ds_read_b128 v[222:225], v197
	v_add_f32_e32 v148, v139, v148
	v_exp_f32_e32 v128, v128
	v_add_f32_e32 v148, v132, v148
	s_waitcnt lgkmcnt(4)
	v_mfma_f32_32x32x16_bf16 v[80:95], v[232:235], v[96:99], v[80:95]
	v_exp_f32_e32 v129, v129
	v_add_f32_e32 v148, v133, v148
	v_exp_f32_e32 v142, v142
	s_waitcnt lgkmcnt(3)
	v_mfma_f32_32x32x16_bf16 v[64:79], v[236:239], v[96:99], v[64:79]
	ds_read_b128 v[232:235], v231
	ds_read_b128 v[236:239], v231 offset:4096
	ds_read_b128 v[226:229], v184
	v_add_f32_e32 v148, v130, v148
	v_exp_f32_e32 v143, v143
	v_add_f32_e32 v148, v131, v148
	v_exp_f32_e32 v136, v136
	s_waitcnt lgkmcnt(3)
	v_mfma_f32_32x32x16_bf16 v[80:95], v[210:213], v[222:225], v[80:95]
	v_add_f32_e32 v148, v128, v148
	v_exp_f32_e32 v137, v137
	v_add_f32_e32 v148, v129, v148
	v_mfma_f32_32x32x16_bf16 v[64:79], v[218:221], v[222:225], v[64:79]
	v_add_u32_e32 v244, s0, v202
	v_add_u32_e32 v247, s0, v204
	ds_read_b128 v[210:213], v244
	ds_read_b128 v[218:221], v244 offset:4096
	ds_read_b128 v[222:225], v183
	v_exp_f32_e32 v134, v134
	v_add_f32_e32 v148, v142, v148
	v_exp_f32_e32 v135, v135
	s_waitcnt lgkmcnt(3)
	v_mfma_f32_32x32x16_bf16 v[80:95], v[232:235], v[226:229], v[80:95]
	v_add_f32_e32 v148, v143, v148
	v_add_f32_e32 v148, v136, v148
	v_add_f32_e32 v148, v137, v148
	v_add_f32_e32 v148, v134, v148
	v_add_f32_e32 v214, v135, v148
	v_mov_b32_e32 v215, v214
	s_nop 1
	v_permlane32_swap_b32_e32 v214, v215
	v_mfma_f32_32x32x16_bf16 v[64:79], v[236:239], v[226:229], v[64:79]
	ds_read_b128 v[232:235], v247
	ds_read_b128 v[236:239], v247 offset:4096
	ds_read_b128 v[226:229], v182
	s_waitcnt lgkmcnt(3)
	v_mfma_f32_32x32x16_bf16 v[80:95], v[210:213], v[222:225], v[80:95]
	v_mfma_f32_32x32x16_bf16 v[64:79], v[218:221], v[222:225], v[64:79]
	v_cvt_pk_bf16_f32 v148, v175, v217
	v_cvt_pk_bf16_f32 v149, v149, v216
	v_cvt_pk_bf16_f32 v150, v150, v174
	v_cvt_pk_bf16_f32 v151, v151, v173
	v_cvt_pk_bf16_f32 v152, v154, v172
	v_cvt_pk_bf16_f32 v153, v153, v155
	s_waitcnt lgkmcnt(0)
	v_mfma_f32_32x32x16_bf16 v[80:95], v[232:235], v[226:229], v[80:95]
	v_cvt_pk_bf16_f32 v154, v145, v147
	v_permlane32_swap_b32_e32 v148, v150
	v_cvt_pk_bf16_f32 v155, v144, v146
	v_permlane32_swap_b32_e32 v152, v154
	v_cvt_pk_bf16_f32 v216, v140, v141
	v_mfma_f32_32x32x16_bf16 v[64:79], v[236:239], v[226:229], v[64:79]
	v_cvt_pk_bf16_f32 v217, v138, v139
	v_cvt_pk_bf16_f32 v218, v132, v133
	v_cvt_pk_bf16_f32 v219, v130, v131
	v_cvt_pk_bf16_f32 v220, v128, v129
	v_cvt_pk_bf16_f32 v221, v142, v143
	v_cvt_pk_bf16_f32 v222, v136, v137
	v_cvt_pk_bf16_f32 v223, v134, v135
	v_permlane32_swap_b32_e32 v149, v151
	v_permlane32_swap_b32_e32 v153, v155
	v_permlane32_swap_b32_e32 v216, v218
	v_permlane32_swap_b32_e32 v217, v219
	v_permlane32_swap_b32_e32 v220, v222
	v_permlane32_swap_b32_e32 v221, v223
	v_lshl_add_u64 v[172:173], s[64:65], 0, v[158:159]
	s_mov_b32 s0, 0x34e80000
	v_add_co_u32_e32 v132, vcc, s0, v172
	s_mov_b32 s0, 0x34ea0000
	s_nop 0
	v_addc_co_u32_e32 v133, vcc, 0, v173, vcc
	v_add_co_u32_e32 v136, vcc, s0, v172
	v_lshl_add_u64 v[174:175], s[64:65], 0, v[170:171]
	s_nop 0
	v_addc_co_u32_e32 v137, vcc, 0, v173, vcc
	global_load_dwordx4 v[128:131], v[132:133], off offset:256
	s_nop 0
	s_nop 0
	global_load_dwordx4 v[140:143], v[136:137], off offset:256
	s_nop 0
	s_mov_b32 s0, 0x1ea04000
	ds_read_b64_tr_b16 v[224:225], v181 offset:0
	ds_read_b64_tr_b16 v[226:227], v181 offset:0x800
	ds_read_b64_tr_b16 v[228:229], v181 offset:0x1000
	ds_read_b64_tr_b16 v[230:231], v181 offset:0x1800
	ds_read_b64_tr_b16 v[232:233], v181 offset:0x2000
	ds_read_b64_tr_b16 v[234:235], v181 offset:0x2800
	ds_read_b64_tr_b16 v[236:237], v181 offset:0x3000
	ds_read_b64_tr_b16 v[238:239], v181 offset:0x3800
	s_nop 0
	s_waitcnt lgkmcnt(6)
	v_mfma_f32_32x32x16_bf16 v[0:15], v[148:151], v[224:227], v[0:15]
	ds_read_b64_tr_b16 v[224:225], v181 offset:0x200
	ds_read_b64_tr_b16 v[226:227], v181 offset:0xa00
	s_waitcnt lgkmcnt(6)
	v_mfma_f32_32x32x16_bf16 v[0:15], v[152:155], v[228:231], v[0:15]
	ds_read_b64_tr_b16 v[228:229], v181 offset:0x1200
	ds_read_b64_tr_b16 v[230:231], v181 offset:0x1a00
	s_waitcnt lgkmcnt(6)
	v_mfma_f32_32x32x16_bf16 v[0:15], v[216:219], v[232:235], v[0:15]
	ds_read_b64_tr_b16 v[232:233], v181 offset:0x2200
	ds_read_b64_tr_b16 v[234:235], v181 offset:0x2a00
	s_waitcnt lgkmcnt(6)
	v_mfma_f32_32x32x16_bf16 v[0:15], v[220:223], v[236:239], v[0:15]
	ds_read_b64_tr_b16 v[236:237], v181 offset:0x3200
	ds_read_b64_tr_b16 v[238:239], v181 offset:0x3a00
	s_waitcnt lgkmcnt(6)
	v_mfma_f32_32x32x16_bf16 v[48:63], v[148:151], v[224:227], v[48:63]
	ds_read_b64_tr_b16 v[224:225], v181 offset:0x400
	ds_read_b64_tr_b16 v[226:227], v181 offset:0xc00
	s_waitcnt lgkmcnt(6)
	v_mfma_f32_32x32x16_bf16 v[48:63], v[152:155], v[228:231], v[48:63]
	ds_read_b64_tr_b16 v[228:229], v181 offset:0x1400
	ds_read_b64_tr_b16 v[230:231], v181 offset:0x1c00
	s_waitcnt lgkmcnt(6)
	v_mfma_f32_32x32x16_bf16 v[48:63], v[216:219], v[232:235], v[48:63]
	ds_read_b64_tr_b16 v[232:233], v181 offset:0x2400
	ds_read_b64_tr_b16 v[234:235], v181 offset:0x2c00
	s_waitcnt lgkmcnt(6)
	v_mfma_f32_32x32x16_bf16 v[48:63], v[220:223], v[236:239], v[48:63]
	ds_read_b64_tr_b16 v[236:237], v181 offset:0x3400
	ds_read_b64_tr_b16 v[238:239], v181 offset:0x3c00
	s_waitcnt lgkmcnt(6)
	v_mfma_f32_32x32x16_bf16 v[32:47], v[148:151], v[224:227], v[32:47]
	ds_read_b64_tr_b16 v[224:225], v181 offset:0x600
	ds_read_b64_tr_b16 v[226:227], v181 offset:0xe00
	s_waitcnt lgkmcnt(6)
	v_mfma_f32_32x32x16_bf16 v[32:47], v[152:155], v[228:231], v[32:47]
	ds_read_b64_tr_b16 v[228:229], v181 offset:0x1600
	ds_read_b64_tr_b16 v[230:231], v181 offset:0x1e00
	s_waitcnt lgkmcnt(6)
	v_mfma_f32_32x32x16_bf16 v[32:47], v[216:219], v[232:235], v[32:47]
	ds_read_b64_tr_b16 v[232:233], v181 offset:0x2600
	ds_read_b64_tr_b16 v[234:235], v181 offset:0x2e00
	s_waitcnt lgkmcnt(6)
	v_mfma_f32_32x32x16_bf16 v[32:47], v[220:223], v[236:239], v[32:47]
	ds_read_b64_tr_b16 v[236:237], v181 offset:0x3600
	ds_read_b64_tr_b16 v[238:239], v181 offset:0x3e00
	s_waitcnt lgkmcnt(6)
	v_mfma_f32_32x32x16_bf16 v[16:31], v[148:151], v[224:227], v[16:31]
	v_max_f32_e32 v148, v81, v81
	v_max_f32_e32 v149, v80, v80
	v_max_f32_e32 v148, v149, v148
	v_max3_f32 v148, v148, v82, v83
	v_max3_f32 v148, v148, v84, v85
	v_max3_f32 v148, v148, v86, v87
	v_max3_f32 v148, v148, v88, v89
	v_max3_f32 v148, v148, v90, v91
	v_max3_f32 v148, v148, v92, v93
	s_waitcnt lgkmcnt(4)
	v_mfma_f32_32x32x16_bf16 v[16:31], v[152:155], v[228:231], v[16:31]
	v_max3_f32 v148, v148, v94, v95
	v_max3_f32 v148, v148, v64, v65
	v_max3_f32 v148, v148, v66, v67
	v_max3_f32 v148, v148, v68, v69
	v_max3_f32 v148, v148, v70, v71
	v_max3_f32 v148, v148, v72, v73
	v_max3_f32 v148, v148, v74, v75
	v_max3_f32 v148, v148, v76, v77
	s_waitcnt lgkmcnt(2)
	v_mfma_f32_32x32x16_bf16 v[16:31], v[216:219], v[232:235], v[16:31]
	v_max3_f32 v148, v148, v78, v79
	v_mov_b32_e32 v149, v148
	s_nop 1
	v_permlane32_swap_b32_e32 v148, v149
	v_max_f32_e32 v149, v149, v149
	v_max_f32_e32 v148, v148, v148
	v_max_f32_e32 v148, v148, v149
	v_sub_f32_e32 v149, v148, v209
	v_cmp_ge_f32_e32 vcc, s90, v149
	v_max_f32_e32 v149, v209, v209
	v_max_f32_e32 v148, v149, v148
	s_waitcnt lgkmcnt(0)
	v_mfma_f32_32x32x16_bf16 v[16:31], v[220:223], v[236:239], v[16:31]
	v_sub_f32_e32 v149, v209, v148
	v_mul_f32_e32 v149, 0x3dd53b94, v149
	v_exp_f32_e32 v149, v149
	s_cmp_eq_u64 vcc, exec
	s_cselect_b64 s[6:7], -1, 0
	s_barrier
	s_waitcnt vmcnt(0)
	v_cndmask_b32_e64 v152, v149, 1.0, s[6:7]
	s_waitcnt vmcnt(4)
	ds_write_b128 v185, v[128:131]
	s_waitcnt vmcnt(2)
	ds_write_b128 v186, v[140:143]
	s_waitcnt vmcnt(1)
	v_add_u32_e32 v128, 0x10000, v207
	v_cmp_gt_f32_e32 vcc, 1.0, v152
	s_waitcnt vmcnt(0)
	s_cbranch_vccz .LBB0_565
	s_and_saveexec_b64 s[0:1], s[4:5]
	ds_write_b32 v178, v152 offset:128
	s_or_b64 exec, exec, s[0:1]
	s_waitcnt lgkmcnt(0)
	v_add_u32_e32 v140, v157, v160
	ds_read_b128 v[128:131], v140 offset:224
	ds_read_b128 v[132:135], v140 offset:192
	ds_read_b128 v[136:139], v140 offset:160
	ds_read_b128 v[140:143], v140 offset:128
	s_waitcnt lgkmcnt(3)
	v_pk_mul_f32 v[12:13], v[12:13], v[128:129]
	s_waitcnt lgkmcnt(2)
	v_pk_mul_f32 v[8:9], v[8:9], v[132:133]
	s_waitcnt lgkmcnt(1)
	v_pk_mul_f32 v[4:5], v[4:5], v[136:137]
	v_pk_mul_f32 v[14:15], v[14:15], v[130:131]
	v_pk_mul_f32 v[10:11], v[10:11], v[134:135]
	v_pk_mul_f32 v[6:7], v[6:7], v[138:139]
	s_waitcnt lgkmcnt(0)
	v_pk_mul_f32 v[2:3], v[2:3], v[142:143]
	v_pk_mul_f32 v[0:1], v[0:1], v[140:141]
	v_pk_mul_f32 v[60:61], v[60:61], v[128:129]
	v_pk_mul_f32 v[56:57], v[56:57], v[132:133]
	v_pk_mul_f32 v[52:53], v[52:53], v[136:137]
	v_pk_mul_f32 v[62:63], v[62:63], v[130:131]
	v_pk_mul_f32 v[58:59], v[58:59], v[134:135]
	v_pk_mul_f32 v[54:55], v[54:55], v[138:139]
	v_pk_mul_f32 v[50:51], v[50:51], v[142:143]
	v_pk_mul_f32 v[48:49], v[48:49], v[140:141]
	v_pk_mul_f32 v[44:45], v[44:45], v[128:129]
	v_pk_mul_f32 v[40:41], v[40:41], v[132:133]
	v_pk_mul_f32 v[36:37], v[36:37], v[136:137]
	v_pk_mul_f32 v[46:47], v[46:47], v[130:131]
	v_pk_mul_f32 v[42:43], v[42:43], v[134:135]
	v_pk_mul_f32 v[38:39], v[38:39], v[138:139]
	v_pk_mul_f32 v[34:35], v[34:35], v[142:143]
	v_pk_mul_f32 v[32:33], v[32:33], v[140:141]
	v_pk_mul_f32 v[28:29], v[28:29], v[128:129]
	v_pk_mul_f32 v[24:25], v[24:25], v[132:133]
	v_pk_mul_f32 v[20:21], v[20:21], v[136:137]
	v_pk_mul_f32 v[30:31], v[30:31], v[130:131]
	v_pk_mul_f32 v[26:27], v[26:27], v[134:135]
	v_pk_mul_f32 v[22:23], v[22:23], v[138:139]
	v_pk_mul_f32 v[18:19], v[18:19], v[142:143]
	v_pk_mul_f32 v[16:17], v[16:17], v[140:141]
.LBB0_565:
	v_cndmask_b32_e64 v153, v148, v209, s[6:7]
	v_mul_f32_e32 v144, 0xbdd53b94, v153
	v_fmamk_f32 v141, v80, 0x3dd53b94, v144
	v_fmamk_f32 v143, v81, 0x3dd53b94, v144
	v_fmamk_f32 v139, v82, 0x3dd53b94, v144
	v_fmamk_f32 v142, v83, 0x3dd53b94, v144
	v_fmamk_f32 v138, v84, 0x3dd53b94, v144
	v_fmamk_f32 v140, v85, 0x3dd53b94, v144
	v_fmamk_f32 v136, v86, 0x3dd53b94, v144
	v_fmamk_f32 v137, v87, 0x3dd53b94, v144
	v_fmamk_f32 v133, v88, 0x3dd53b94, v144
	v_fmamk_f32 v135, v89, 0x3dd53b94, v144
	v_fmamk_f32 v132, v90, 0x3dd53b94, v144
	v_fmamk_f32 v134, v91, 0x3dd53b94, v144
	v_fmamk_f32 v129, v92, 0x3dd53b94, v144
	v_fmamk_f32 v131, v93, 0x3dd53b94, v144
	v_fmamk_f32 v128, v94, 0x3dd53b94, v144
	v_fmamk_f32 v130, v95, 0x3dd53b94, v144
	v_fmamk_f32 v218, v68, 0x3dd53b94, v144
	v_fmamk_f32 v148, v71, 0x3dd53b94, v144
	v_fmamk_f32 v149, v72, 0x3dd53b94, v144
	v_fmamk_f32 v219, v77, 0x3dd53b94, v144
	v_fmamk_f32 v155, v64, 0x3dd53b94, v144
	v_fmamk_f32 v209, v65, 0x3dd53b94, v144
	v_fmamk_f32 v216, v66, 0x3dd53b94, v144
	v_fmamk_f32 v217, v67, 0x3dd53b94, v144
	v_fmamk_f32 v146, v69, 0x3dd53b94, v144
	v_fmamk_f32 v147, v70, 0x3dd53b94, v144
	v_fmamk_f32 v150, v73, 0x3dd53b94, v144
	v_fmamk_f32 v151, v74, 0x3dd53b94, v144
	v_fmamk_f32 v154, v75, 0x3dd53b94, v144
	v_fmamk_f32 v145, v76, 0x3dd53b94, v144
	v_fmamk_f32 v220, v78, 0x3dd53b94, v144
	v_fmac_f32_e32 v144, 0x3dd53b94, v79
	s_waitcnt lgkmcnt(0)
	s_barrier
	ds_read_b128 v[64:67], v189 offset:32768
	ds_read_b128 v[68:71], v189 offset:40960
	ds_read_b128 v[222:225], v190 offset:32768
	ds_read_b128 v[226:229], v190 offset:40960
	v_exp_f32_e32 v155, v155
	v_exp_f32_e32 v209, v209
	s_waitcnt lgkmcnt(3)
	v_mfma_f32_32x32x16_bf16 v[80:95], v[64:67], v[120:123], 0
	v_xor_b32_e32 v241, v243, v158
	s_add_u32 s100, s64, 0x34ec0000
	s_addc_u32 s101, s65, 0
	s_lshl_b32 m0, s33, 4
	s_add_i32 m0, m0, 0xc000
	s_nop 0
	global_load_lds_dwordx4 v241, s[100:101]
	s_add_u32 s100, s64, 0x34ee0000
	s_addc_u32 s101, s65, 0
	s_add_i32 m0, m0, 0x2000
	s_nop 0
	global_load_lds_dwordx4 v241, s[100:101]
	v_xor_b32_e32 v241, v242, v170
	s_add_u32 s100, s64, 0x1ea06000
	s_addc_u32 s101, s65, 0
	s_add_i32 m0, m0, 0x4000
	s_nop 0
	global_load_lds_dwordx4 v241, s[100:101]
	v_exp_f32_e32 v216, v216
	v_exp_f32_e32 v217, v217
	s_waitcnt lgkmcnt(2)
	v_mfma_f32_32x32x16_bf16 v[64:79], v[68:71], v[120:123], 0
	v_exp_f32_e32 v141, v141
	v_exp_f32_e32 v143, v143
	v_add_f32_e32 v240, 0, v141
	v_exp_f32_e32 v139, v139
	v_add_f32_e32 v240, v143, v240
	s_waitcnt lgkmcnt(0)
	v_mfma_f32_32x32x16_bf16 v[64:79], v[226:229], v[124:127], v[64:79]
	v_exp_f32_e32 v142, v142
	v_add_f32_e32 v240, v139, v240
	v_exp_f32_e32 v138, v138
	v_add_f32_e32 v240, v142, v240
	v_mfma_f32_32x32x16_bf16 v[80:95], v[222:225], v[124:127], v[80:95]
	v_exp_f32_e32 v146, v146
	v_exp_f32_e32 v140, v140
	v_add_f32_e32 v240, v138, v240
	ds_read_b128 v[222:225], v191 offset:32768
	ds_read_b128 v[226:229], v191 offset:40960
	s_waitcnt lgkmcnt(0)
	v_mfma_f32_32x32x16_bf16 v[64:79], v[226:229], v[116:119], v[64:79]
	v_exp_f32_e32 v136, v136
	v_add_f32_e32 v240, v140, v240
	v_exp_f32_e32 v147, v147
	v_mfma_f32_32x32x16_bf16 v[80:95], v[222:225], v[116:119], v[80:95]
	v_exp_f32_e32 v137, v137
	v_add_f32_e32 v240, v136, v240
	v_exp_f32_e32 v133, v133
	v_add_f32_e32 v240, v137, v240
	ds_read_b128 v[222:225], v192 offset:32768
	ds_read_b128 v[226:229], v192 offset:40960
	s_waitcnt lgkmcnt(0)
	v_mfma_f32_32x32x16_bf16 v[64:79], v[226:229], v[112:115], v[64:79]
	v_exp_f32_e32 v154, v154
	v_exp_f32_e32 v135, v135
	v_add_f32_e32 v240, v133, v240
	v_mfma_f32_32x32x16_bf16 v[80:95], v[222:225], v[112:115], v[80:95]
	v_exp_f32_e32 v132, v132
	v_add_f32_e32 v240, v135, v240
	v_exp_f32_e32 v145, v145
	ds_read_b128 v[222:225], v193 offset:32768
	ds_read_b128 v[226:229], v193 offset:40960
	s_waitcnt lgkmcnt(0)
	v_mfma_f32_32x32x16_bf16 v[64:79], v[226:229], v[108:111], v[64:79]
	v_exp_f32_e32 v134, v134
	v_add_f32_e32 v240, v132, v240
	v_exp_f32_e32 v129, v129
	v_add_f32_e32 v240, v134, v240
	v_mfma_f32_32x32x16_bf16 v[80:95], v[222:225], v[108:111], v[80:95]
	v_exp_f32_e32 v144, v144
	v_exp_f32_e32 v131, v131
	v_add_f32_e32 v240, v129, v240
	ds_read_b128 v[222:225], v194 offset:32768
	ds_read_b128 v[226:229], v194 offset:40960
	s_waitcnt lgkmcnt(0)
	v_mfma_f32_32x32x16_bf16 v[64:79], v[226:229], v[104:107], v[64:79]
	v_exp_f32_e32 v128, v128
	v_add_f32_e32 v240, v131, v240
	v_exp_f32_e32 v218, v218
	v_mfma_f32_32x32x16_bf16 v[80:95], v[222:225], v[104:107], v[80:95]
	v_exp_f32_e32 v130, v130
	v_add_f32_e32 v240, v128, v240
	v_add_f32_e32 v240, v130, v240
	ds_read_b128 v[222:225], v195 offset:32768
	ds_read_b128 v[226:229], v195 offset:40960
	s_waitcnt lgkmcnt(0)
	v_mfma_f32_32x32x16_bf16 v[64:79], v[226:229], v[100:103], v[64:79]
	v_exp_f32_e32 v148, v148
	v_add_f32_e32 v240, v155, v240
	v_mfma_f32_32x32x16_bf16 v[80:95], v[222:225], v[100:103], v[80:95]
	v_add_f32_e32 v240, v209, v240
	v_exp_f32_e32 v149, v149
	ds_read_b128 v[222:225], v196 offset:32768
	ds_read_b128 v[226:229], v196 offset:40960
	s_waitcnt lgkmcnt(0)
	v_mfma_f32_32x32x16_bf16 v[64:79], v[226:229], v[96:99], v[64:79]
	v_add_f32_e32 v240, v216, v240
	v_add_f32_e32 v240, v217, v240
	v_mfma_f32_32x32x16_bf16 v[80:95], v[222:225], v[96:99], v[80:95]
	v_exp_f32_e32 v150, v150
	v_add_f32_e32 v240, v218, v240
	ds_read_b128 v[222:225], v199
	ds_read_b128 v[226:229], v199 offset:4096
	ds_read_b128 v[230:233], v197
	s_waitcnt lgkmcnt(0)
	v_mfma_f32_32x32x16_bf16 v[64:79], v[226:229], v[230:233], v[64:79]
	v_add_f32_e32 v240, v146, v240
	v_exp_f32_e32 v151, v151
	v_mfma_f32_32x32x16_bf16 v[80:95], v[222:225], v[230:233], v[80:95]
	v_add_f32_e32 v240, v147, v240
	v_add_f32_e32 v240, v148, v240
	ds_read_b128 v[222:225], v201
	ds_read_b128 v[226:229], v201 offset:4096
	ds_read_b128 v[230:233], v184
	s_waitcnt lgkmcnt(0)
	v_mfma_f32_32x32x16_bf16 v[64:79], v[226:229], v[230:233], v[64:79]
	v_exp_f32_e32 v219, v219
	v_add_f32_e32 v240, v149, v240
	v_mfma_f32_32x32x16_bf16 v[80:95], v[222:225], v[230:233], v[80:95]
	v_add_f32_e32 v240, v150, v240
	v_exp_f32_e32 v220, v220
	ds_read_b128 v[222:225], v203
	ds_read_b128 v[226:229], v203 offset:4096
	ds_read_b128 v[230:233], v183
	s_waitcnt lgkmcnt(0)
	v_mfma_f32_32x32x16_bf16 v[64:79], v[226:229], v[230:233], v[64:79]
	v_add_f32_e32 v240, v151, v240
	v_add_f32_e32 v240, v154, v240
	v_mfma_f32_32x32x16_bf16 v[80:95], v[222:225], v[230:233], v[80:95]
	v_add_f32_e32 v240, v145, v240
	v_add_f32_e32 v240, v219, v240
	ds_read_b128 v[222:225], v205
	ds_read_b128 v[226:229], v205 offset:4096
	ds_read_b128 v[230:233], v182
	s_waitcnt lgkmcnt(0)
	v_mfma_f32_32x32x16_bf16 v[64:79], v[226:229], v[230:233], v[64:79]
	v_add_f32_e32 v240, v220, v240
	v_add_f32_e32 v240, v144, v240
	v_mfma_f32_32x32x16_bf16 v[80:95], v[222:225], v[230:233], v[80:95]
	v_cvt_pk_bf16_f32 v226, v218, v146
	v_cvt_pk_bf16_f32 v227, v147, v148
	v_cvt_pk_bf16_f32 v228, v149, v150
	v_cvt_pk_bf16_f32 v229, v151, v154
	v_cvt_pk_bf16_f32 v230, v145, v219
	v_cvt_pk_bf16_f32 v231, v220, v144
	v_mov_b32_e32 v218, v240
	v_mov_b32_e32 v219, v240
	v_cvt_pk_bf16_f32 v148, v141, v143
	v_cvt_pk_bf16_f32 v149, v139, v142
	v_cvt_pk_bf16_f32 v150, v138, v140
	v_cvt_pk_bf16_f32 v151, v136, v137
	v_permlane32_swap_b32_e32 v218, v219
	v_permlane32_swap_b32_e32 v148, v150
	v_permlane32_swap_b32_e32 v149, v151
	v_cvt_pk_bf16_f32 v220, v133, v135
	v_cvt_pk_bf16_f32 v221, v132, v134
	v_cvt_pk_bf16_f32 v222, v129, v131
	v_cvt_pk_bf16_f32 v223, v128, v130
	v_cvt_pk_bf16_f32 v224, v155, v209
	v_cvt_pk_bf16_f32 v225, v216, v217
	s_nop 0
	v_permlane32_swap_b32_e32 v220, v222
	v_permlane32_swap_b32_e32 v221, v223
	v_permlane32_swap_b32_e32 v224, v226
	v_permlane32_swap_b32_e32 v225, v227
	v_permlane32_swap_b32_e32 v228, v230
	v_permlane32_swap_b32_e32 v229, v231
	s_mov_b32 s0, 0x34ec0000
	v_add_co_u32_e32 v132, vcc, s0, v172
	s_mov_b32 s0, 0x34ee0000
	s_nop 0
	v_addc_co_u32_e32 v133, vcc, 0, v173, vcc
	v_add_co_u32_e32 v136, vcc, s0, v172
	s_mov_b32 s0, 0x1ea06000
	s_nop 0
	v_addc_co_u32_e32 v137, vcc, 0, v173, vcc
	global_load_dwordx4 v[128:131], v[132:133], off offset:256
	s_nop 0
	s_nop 0
	global_load_dwordx4 v[140:143], v[136:137], off offset:256
	s_nop 0
	ds_read_b64_tr_b16 v[172:173], v180 offset:0
	ds_read_b64_tr_b16 v[174:175], v180 offset:0x800
	ds_read_b64_tr_b16 v[232:233], v180 offset:0x1000
	ds_read_b64_tr_b16 v[234:235], v180 offset:0x1800
	ds_read_b64_tr_b16 v[236:237], v180 offset:0x2000
	ds_read_b64_tr_b16 v[238:239], v180 offset:0x2800
	ds_read_b64_tr_b16 v[248:249], v180 offset:0x3000
	ds_read_b64_tr_b16 v[250:251], v180 offset:0x3800
	s_nop 0
	s_waitcnt lgkmcnt(6)
	v_mfma_f32_32x32x16_bf16 v[0:15], v[148:151], v[172:175], v[0:15]
	ds_read_b64_tr_b16 v[172:173], v180 offset:0x200
	ds_read_b64_tr_b16 v[174:175], v180 offset:0xa00
	s_waitcnt lgkmcnt(6)
	v_mfma_f32_32x32x16_bf16 v[0:15], v[220:223], v[232:235], v[0:15]
	ds_read_b64_tr_b16 v[232:233], v180 offset:0x1200
	ds_read_b64_tr_b16 v[234:235], v180 offset:0x1a00
	s_waitcnt lgkmcnt(6)
	v_mfma_f32_32x32x16_bf16 v[0:15], v[224:227], v[236:239], v[0:15]
	ds_read_b64_tr_b16 v[236:237], v180 offset:0x2200
	ds_read_b64_tr_b16 v[238:239], v180 offset:0x2a00
	s_waitcnt lgkmcnt(6)
	v_mfma_f32_32x32x16_bf16 v[0:15], v[228:231], v[248:251], v[0:15]
	ds_read_b64_tr_b16 v[248:249], v180 offset:0x3200
	ds_read_b64_tr_b16 v[250:251], v180 offset:0x3a00
	s_waitcnt lgkmcnt(6)
	v_mfma_f32_32x32x16_bf16 v[48:63], v[148:151], v[172:175], v[48:63]
	ds_read_b64_tr_b16 v[172:173], v180 offset:0x400
	ds_read_b64_tr_b16 v[174:175], v180 offset:0xc00
	s_waitcnt lgkmcnt(6)
	v_mfma_f32_32x32x16_bf16 v[48:63], v[220:223], v[232:235], v[48:63]
	ds_read_b64_tr_b16 v[232:233], v180 offset:0x1400
	ds_read_b64_tr_b16 v[234:235], v180 offset:0x1c00
	s_waitcnt lgkmcnt(6)
	v_mfma_f32_32x32x16_bf16 v[48:63], v[224:227], v[236:239], v[48:63]
	ds_read_b64_tr_b16 v[236:237], v180 offset:0x2400
	ds_read_b64_tr_b16 v[238:239], v180 offset:0x2c00
	s_waitcnt lgkmcnt(6)
	v_mfma_f32_32x32x16_bf16 v[48:63], v[228:231], v[248:251], v[48:63]
	ds_read_b64_tr_b16 v[248:249], v180 offset:0x3400
	ds_read_b64_tr_b16 v[250:251], v180 offset:0x3c00
	s_waitcnt lgkmcnt(6)
	v_mfma_f32_32x32x16_bf16 v[32:47], v[148:151], v[172:175], v[32:47]
	ds_read_b64_tr_b16 v[172:173], v180 offset:0x600
	ds_read_b64_tr_b16 v[174:175], v180 offset:0xe00
	s_waitcnt lgkmcnt(6)
	v_mfma_f32_32x32x16_bf16 v[32:47], v[220:223], v[232:235], v[32:47]
	ds_read_b64_tr_b16 v[232:233], v180 offset:0x1600
	ds_read_b64_tr_b16 v[234:235], v180 offset:0x1e00
	s_waitcnt lgkmcnt(6)
	v_mfma_f32_32x32x16_bf16 v[32:47], v[224:227], v[236:239], v[32:47]
	ds_read_b64_tr_b16 v[236:237], v180 offset:0x2600
	ds_read_b64_tr_b16 v[238:239], v180 offset:0x2e00
	s_waitcnt lgkmcnt(6)
	v_mfma_f32_32x32x16_bf16 v[32:47], v[228:231], v[248:251], v[32:47]
	ds_read_b64_tr_b16 v[248:249], v180 offset:0x3600
	ds_read_b64_tr_b16 v[250:251], v180 offset:0x3e00
	s_waitcnt lgkmcnt(6)
	v_mfma_f32_32x32x16_bf16 v[16:31], v[148:151], v[172:175], v[16:31]
	v_max_f32_e32 v148, v81, v81
	v_max_f32_e32 v149, v80, v80
	v_max_f32_e32 v148, v149, v148
	v_max3_f32 v148, v148, v82, v83
	v_max3_f32 v148, v148, v84, v85
	v_max3_f32 v148, v148, v86, v87
	v_max3_f32 v148, v148, v88, v89
	v_max3_f32 v148, v148, v90, v91
	v_max3_f32 v148, v148, v92, v93
	s_waitcnt lgkmcnt(4)
	v_mfma_f32_32x32x16_bf16 v[16:31], v[220:223], v[232:235], v[16:31]
	v_max3_f32 v148, v148, v94, v95
	v_max3_f32 v148, v148, v64, v65
	v_max3_f32 v148, v148, v66, v67
	v_max3_f32 v148, v148, v68, v69
	v_max3_f32 v148, v148, v70, v71
	v_max3_f32 v148, v148, v72, v73
	v_max3_f32 v148, v148, v74, v75
	v_max3_f32 v148, v148, v76, v77
	s_waitcnt lgkmcnt(2)
	v_mfma_f32_32x32x16_bf16 v[16:31], v[224:227], v[236:239], v[16:31]
	v_max3_f32 v148, v148, v78, v79
	v_mov_b32_e32 v149, v148
	s_nop 1
	v_permlane32_swap_b32_e32 v148, v149
	v_max_f32_e32 v149, v149, v149
	v_max_f32_e32 v148, v148, v148
	v_max_f32_e32 v148, v148, v149
	v_sub_f32_e32 v149, v148, v153
	v_cmp_ge_f32_e32 vcc, s90, v149
	v_max_f32_e32 v149, v153, v153
	v_max_f32_e32 v149, v149, v148
	s_waitcnt lgkmcnt(0)
	v_mfma_f32_32x32x16_bf16 v[16:31], v[228:231], v[248:251], v[16:31]
	v_sub_f32_e32 v148, v153, v149
	v_mul_f32_e32 v148, 0x3dd53b94, v148
	v_exp_f32_e32 v148, v148
	s_cmp_eq_u64 vcc, exec
	s_cselect_b64 s[6:7], -1, 0
	s_barrier
	s_waitcnt vmcnt(0)
	v_cndmask_b32_e64 v148, v148, 1.0, s[6:7]
	v_cmp_gt_f32_e32 vcc, 1.0, v148
	s_waitcnt vmcnt(4)
	ds_write_b128 v185, v[128:131] offset:16384
	s_waitcnt vmcnt(2)
	ds_write_b128 v186, v[140:143] offset:16384
	s_waitcnt vmcnt(1)
	s_waitcnt vmcnt(0)
	s_cbranch_vccz .LBB0_569
	s_and_saveexec_b64 s[0:1], s[4:5]
	ds_write_b32 v178, v148 offset:128
	s_or_b64 exec, exec, s[0:1]
	s_waitcnt lgkmcnt(0)
	v_add_u32_e32 v140, v157, v160
	ds_read_b128 v[128:131], v140 offset:224
	ds_read_b128 v[132:135], v140 offset:192
	ds_read_b128 v[136:139], v140 offset:160
	ds_read_b128 v[140:143], v140 offset:128
	s_waitcnt lgkmcnt(3)
	v_pk_mul_f32 v[12:13], v[12:13], v[128:129]
	s_waitcnt lgkmcnt(2)
	v_pk_mul_f32 v[8:9], v[8:9], v[132:133]
	s_waitcnt lgkmcnt(1)
	v_pk_mul_f32 v[4:5], v[4:5], v[136:137]
	v_pk_mul_f32 v[14:15], v[14:15], v[130:131]
	v_pk_mul_f32 v[10:11], v[10:11], v[134:135]
	v_pk_mul_f32 v[6:7], v[6:7], v[138:139]
	s_waitcnt lgkmcnt(0)
	v_pk_mul_f32 v[2:3], v[2:3], v[142:143]
	v_pk_mul_f32 v[0:1], v[0:1], v[140:141]
	v_pk_mul_f32 v[60:61], v[60:61], v[128:129]
	v_pk_mul_f32 v[56:57], v[56:57], v[132:133]
	v_pk_mul_f32 v[52:53], v[52:53], v[136:137]
	v_pk_mul_f32 v[62:63], v[62:63], v[130:131]
	v_pk_mul_f32 v[58:59], v[58:59], v[134:135]
	v_pk_mul_f32 v[54:55], v[54:55], v[138:139]
	v_pk_mul_f32 v[50:51], v[50:51], v[142:143]
	v_pk_mul_f32 v[48:49], v[48:49], v[140:141]
	v_pk_mul_f32 v[44:45], v[44:45], v[128:129]
	v_pk_mul_f32 v[40:41], v[40:41], v[132:133]
	v_pk_mul_f32 v[36:37], v[36:37], v[136:137]
	v_pk_mul_f32 v[46:47], v[46:47], v[130:131]
	v_pk_mul_f32 v[42:43], v[42:43], v[134:135]
	v_pk_mul_f32 v[38:39], v[38:39], v[138:139]
	v_pk_mul_f32 v[34:35], v[34:35], v[142:143]
	v_pk_mul_f32 v[32:33], v[32:33], v[140:141]
	v_pk_mul_f32 v[28:29], v[28:29], v[128:129]
	v_pk_mul_f32 v[24:25], v[24:25], v[132:133]
	v_pk_mul_f32 v[20:21], v[20:21], v[136:137]
	v_pk_mul_f32 v[30:31], v[30:31], v[130:131]
	v_pk_mul_f32 v[26:27], v[26:27], v[134:135]
	v_pk_mul_f32 v[22:23], v[22:23], v[138:139]
	v_pk_mul_f32 v[18:19], v[18:19], v[142:143]
	v_pk_mul_f32 v[16:17], v[16:17], v[140:141]
